# dilated attention: second LDS K/V image for the odd pipeline step, barrier in front of each tile's LDS writes removed (one s_barrier per 128-key tile instead of two); on v067
# speedup vs baseline: 1.0045x; 1.0045x over previous
.LBB0_444:
	s_and_b64 vcc, exec, s[0:1]
	s_cbranch_vccz .LBB0_353
	s_add_u32 s4, s42, 0x2000000
	s_addc_u32 s5, s43, 0
	v_mov_b32_e32 v8, v194
	s_add_u32 s6, s42, 0x4000000
	s_addc_u32 s7, s43, 0
	v_readfirstlane_b32 s0, v8
	s_ashr_i32 s0, s0, 1
	s_lshl_b32 s8, s56, 8
	s_and_b32 s56, s0, 0xffffffe0
	v_and_b32_e32 v9, 31, v8
	s_add_i32 s56, s56, s8
	v_or_b32_e32 v130, s56, v9
	v_ashrrev_i32_e32 v131, 31, v130
	v_bfe_u32 v10, v8, 5, 1
	v_lshlrev_b64 v[0:1], 7, v[130:131]
	v_lshl_add_u64 v[0:1], s[42:43], 0, v[0:1]
	v_lshlrev_b32_e32 v128, 4, v10
	v_lshl_add_u64 v[0:1], v[0:1], 0, v[128:129]
	v_and_b32_e32 v11, 3, v8
	global_load_dwordx4 v[64:67], v[0:1], off
	global_load_dwordx4 v[68:71], v[0:1], off offset:32
	global_load_dwordx4 v[72:75], v[0:1], off offset:64
	global_load_dwordx4 v[76:79], v[0:1], off offset:96
	v_bfe_u32 v0, v8, 3, 1
	v_bfe_u32 v1, v9, 2, 1
	v_or_b32_e32 v2, v0, v11
	v_cmp_eq_u32_e32 vcc, 0, v2
	v_cmp_eq_u32_e64 s[0:1], v10, v1
	s_and_b64 s[2:3], s[0:1], vcc
	v_cndmask_b32_e64 v132, 0, 1.0, s[2:3]
	v_cmp_eq_u32_e64 s[2:3], 1, v11
	v_cmp_eq_u32_e32 vcc, 0, v0
	s_and_b64 s[42:43], s[2:3], s[0:1]
	v_cndmask_b32_e64 v135, 0, 1.0, s[2:3]
	s_and_b64 s[2:3], s[42:43], vcc
	v_cndmask_b32_e64 v133, 0, 1.0, s[2:3]
	v_cmp_eq_u32_e64 s[2:3], 2, v11
	s_and_b64 s[58:59], s[2:3], s[0:1]
	v_mov_b32_e32 v205, 0xff800000
	v_cndmask_b32_e64 v136, 0, 1.0, s[2:3]
	s_and_b64 s[2:3], s[58:59], vcc
	v_cndmask_b32_e64 v138, 0, 1.0, s[2:3]
	v_cmp_eq_u32_e64 s[2:3], 3, v11
	s_and_b64 s[60:61], s[2:3], s[0:1]
	v_and_b32_e32 v0, 8, v8
	v_cndmask_b32_e64 v137, 0, 1.0, s[2:3]
	s_and_b64 s[2:3], s[60:61], vcc
	v_cndmask_b32_e64 v139, 0, 1.0, s[2:3]
	v_cmp_eq_u32_e64 s[2:3], 0, v11
	v_cndmask_b32_e64 v196, v205, 0, s[0:1]
	v_cmp_ne_u32_e32 vcc, 0, v0
	s_and_b64 s[0:1], s[2:3], s[0:1]
	s_and_b64 s[0:1], s[0:1], vcc
	v_cndmask_b32_e64 v140, 0, 1.0, s[0:1]
	s_and_b64 s[0:1], s[42:43], vcc
	v_mul_u32_u24_e32 v0, 12, v10
	v_mad_u32_u24 v1, v10, 12, v8
	v_cndmask_b32_e64 v141, 0, 1.0, s[0:1]
	s_and_b64 s[0:1], s[58:59], vcc
	v_and_b32_e32 v1, 12, v1
	v_xad_u32 v0, v0, 8, v8
	v_cndmask_b32_e64 v142, 0, 1.0, s[0:1]
	s_and_b64 s[0:1], s[60:61], vcc
	v_cmp_eq_u32_e32 vcc, 0, v1
	v_and_b32_e32 v0, 12, v0
	v_lshlrev_b32_e32 v197, 2, v10
	v_cndmask_b32_e64 v145, 1.0, 2.0, vcc
	v_cmp_eq_u32_e32 vcc, 0, v0
	v_sub_u32_e32 v0, v8, v197
	v_and_b32_e32 v0, 15, v0
	v_cndmask_b32_e64 v144, 1.0, 2.0, vcc
	v_cmp_eq_u32_e32 vcc, 0, v0
	v_cndmask_b32_e64 v1, 1.0, 2.0, s[2:3]
	v_cndmask_b32_e64 v143, 0, 1.0, s[0:1]
	v_cndmask_b32_e64 v0, 0, 1.0, vcc
	v_add_f32_e32 v149, v1, v0
	v_xad_u32 v0, v197, -1, v9
	v_and_b32_e32 v2, 15, v0
	v_and_b32_e32 v0, 3, v0
	v_cmp_eq_u32_e32 vcc, 0, v0
	s_or_b32 s0, s8, 0xff
	s_and_b32 s1, s0, 0x780
	v_cndmask_b32_e64 v0, 1.0, 2.0, vcc
	v_cmp_eq_u32_e32 vcc, 0, v2
	v_cndmask_b32_e64 v134, 0, 1.0, s[2:3]
	v_mov_b32_e32 v147, v145
	v_cndmask_b32_e64 v2, 0, 1.0, vcc
	v_add_f32_e32 v148, v0, v2
	v_or_b32_e32 v0, 2, v197
	v_sub_u32_e32 v0, v9, v0
	v_and_b32_e32 v2, 15, v0
	v_and_b32_e32 v0, 3, v0
	v_cmp_eq_u32_e32 vcc, 0, v0
	v_mov_b32_e32 v146, v144
	v_mov_b32_e32 v150, v149
	v_cndmask_b32_e64 v0, 1.0, 2.0, vcc
	v_cmp_eq_u32_e32 vcc, 0, v2
	v_mov_b32_e32 v151, v148
	s_nop 0
	v_cndmask_b32_e64 v2, 0, 1.0, vcc
	v_add_f32_e32 v153, v0, v2
	v_or_b32_e32 v0, 3, v197
	v_sub_u32_e32 v0, v9, v0
	v_and_b32_e32 v2, 15, v0
	v_and_b32_e32 v0, 3, v0
	v_cmp_eq_u32_e32 vcc, 0, v0
	v_mov_b32_e32 v154, v153
	s_nop 0
	v_cndmask_b32_e64 v0, 1.0, 2.0, vcc
	v_cmp_eq_u32_e32 vcc, 0, v2
	s_nop 1
	v_cndmask_b32_e64 v2, 0, 1.0, vcc
	v_add_f32_e32 v152, v0, v2
	v_xor_b32_e32 v0, 8, v8
	v_sub_u32_e32 v0, v0, v197
	v_and_b32_e32 v0, 15, v0
	v_cmp_eq_u32_e32 vcc, 0, v0
	v_mov_b32_e32 v155, v152
	s_nop 0
	v_cndmask_b32_e64 v0, 0, 1.0, vcc
	v_add_f32_e32 v157, v1, v0
	v_or_b32_e32 v0, 9, v197
	v_sub_u32_e32 v0, v9, v0
	v_and_b32_e32 v1, 15, v0
	v_and_b32_e32 v0, 3, v0
	v_cmp_eq_u32_e32 vcc, 0, v0
	v_mov_b32_e32 v159, v157
	s_nop 0
	v_cndmask_b32_e64 v0, 1.0, 2.0, vcc
	v_cmp_eq_u32_e32 vcc, 0, v1
	v_mad_u32_u24 v20, v9, s47, 0
	v_mov_b32_e32 v14, v129
	v_cndmask_b32_e64 v1, 0, 1.0, vcc
	v_add_f32_e32 v156, v0, v1
	v_or_b32_e32 v0, 10, v197
	v_sub_u32_e32 v0, v9, v0
	v_and_b32_e32 v1, 15, v0
	v_and_b32_e32 v0, 3, v0
	v_cmp_eq_u32_e32 vcc, 0, v0
	v_mov_b32_e32 v158, v156
	v_mov_b32_e32 v15, v129
	v_cndmask_b32_e64 v0, 1.0, 2.0, vcc
	v_cmp_eq_u32_e32 vcc, 0, v1
	v_lshlrev_b32_e32 v164, 3, v10
	v_cmp_eq_u16_e64 s[8:9], 3, v11
	v_cndmask_b32_e64 v1, 0, 1.0, vcc
	v_add_f32_e32 v161, v0, v1
	v_or_b32_e32 v0, 11, v197
	v_sub_u32_e32 v0, v9, v0
	v_and_b32_e32 v1, 15, v0
	v_and_b32_e32 v0, 3, v0
	v_cmp_eq_u32_e32 vcc, 0, v0
	v_mov_b32_e32 v163, v161
	v_mov_b32_e32 v9, v129
	v_cndmask_b32_e64 v0, 1.0, 2.0, vcc
	v_cmp_eq_u32_e32 vcc, 0, v1
	v_mov_b32_e32 v10, v129
	v_add_u32_e32 v202, v20, v128
	v_cndmask_b32_e64 v1, 0, 1.0, vcc
	v_add_f32_e32 v160, v0, v1
	v_ashrrev_i32_e32 v0, 31, v8
	v_lshrrev_b32_e32 v0, 29, v0
	v_add_u32_e32 v0, v8, v0
	v_ashrrev_i32_e32 v198, 3, v0
	v_and_b32_e32 v0, -8, v0
	v_sub_u32_e32 v12, v8, v0
	v_add_u32_e32 v0, s1, v198
	v_ashrrev_i32_e32 v1, 31, v0
	v_lshlrev_b32_e32 v4, 3, v12
	v_lshlrev_b64 v[0:1], 7, v[0:1]
	v_ashrrev_i32_e32 v5, 31, v4
	v_lshl_add_u64 v[2:3], s[4:5], 0, v[0:1]
	v_lshlrev_b64 v[4:5], 1, v[4:5]
	v_lshl_add_u64 v[0:1], s[6:7], 0, v[0:1]
	v_mov_b32_e32 v162, v160
	v_lshl_add_u64 v[2:3], v[2:3], 0, v[4:5]
	v_lshl_add_u64 v[0:1], v[0:1], 0, v[4:5]
	global_load_dwordx4 v[80:83], v[2:3], off
	global_load_dwordx4 v[84:87], v[0:1], off
	v_add_u32_e32 v0, 0x200, v8
	v_ashrrev_i32_e32 v1, 31, v0
	v_lshrrev_b32_e32 v1, 29, v1
	v_add_u32_e32 v1, v0, v1
	v_ashrrev_i32_e32 v199, 3, v1
	v_and_b32_e32 v1, -8, v1
	v_sub_u32_e32 v13, v0, v1
	v_add_u32_e32 v0, s1, v199
	v_ashrrev_i32_e32 v1, 31, v0
	v_lshlrev_b32_e32 v6, 3, v13
	v_lshlrev_b64 v[0:1], 7, v[0:1]
	v_ashrrev_i32_e32 v7, 31, v6
	v_lshl_add_u64 v[2:3], s[4:5], 0, v[0:1]
	v_lshlrev_b64 v[6:7], 1, v[6:7]
	v_lshl_add_u64 v[0:1], s[6:7], 0, v[0:1]
	v_lshl_add_u64 v[2:3], v[2:3], 0, v[6:7]
	v_lshl_add_u64 v[0:1], v[0:1], 0, v[6:7]
	s_addk_i32 s1, 0xff80
	global_load_dwordx4 v[88:91], v[2:3], off
	global_load_dwordx4 v[92:95], v[0:1], off
	v_add_u32_e32 v0, s1, v198
	v_ashrrev_i32_e32 v1, 31, v0
	v_lshlrev_b64 v[0:1], 7, v[0:1]
	v_lshl_add_u64 v[2:3], s[4:5], 0, v[0:1]
	v_lshl_add_u64 v[0:1], s[6:7], 0, v[0:1]
	v_lshl_add_u64 v[2:3], v[2:3], 0, v[4:5]
	v_lshl_add_u64 v[0:1], v[0:1], 0, v[4:5]
	global_load_dwordx4 v[96:99], v[2:3], off
	global_load_dwordx4 v[100:103], v[0:1], off
	v_add_u32_e32 v0, s1, v199
	v_ashrrev_i32_e32 v1, 31, v0
	v_lshlrev_b64 v[0:1], 7, v[0:1]
	v_lshl_add_u64 v[2:3], s[4:5], 0, v[0:1]
	v_lshl_add_u64 v[2:3], v[2:3], 0, v[6:7]
	v_lshl_add_u64 v[0:1], s[6:7], 0, v[0:1]
	v_lshl_add_u64 v[0:1], v[0:1], 0, v[6:7]
	global_load_dwordx4 v[104:107], v[2:3], off
	global_load_dwordx4 v[108:111], v[0:1], off
	v_mul_lo_u32 v1, v198, s47
	v_add_u32_e32 v16, 0, v1
	v_mul_lo_u32 v1, v199, s47
	v_bfe_u32 v0, v8, 2, 3
	v_add_u32_e32 v18, 0, v1
	v_lshlrev_b32_e32 v1, 1, v8
	v_and_or_b32 v0, v0, 3, v197
	v_and_b32_e32 v1, 32, v1
	v_lshlrev_b32_e32 v2, 3, v11
	v_lshlrev_b32_e32 v17, 4, v12
	v_lshlrev_b32_e32 v19, 4, v13
	v_add3_u32 v21, 0, v1, v2
	v_mul_u32_u24_e32 v22, 0x90, v0
	v_lshl_add_u64 v[166:167], s[4:5], 0, v[4:5]
	v_lshl_add_u64 v[168:169], s[6:7], 0, v[4:5]
	v_lshl_add_u64 v[170:171], s[4:5], 0, v[6:7]
	v_lshl_add_u64 v[172:173], s[6:7], 0, v[6:7]
	v_cmp_eq_u16_e64 s[4:5], 1, v11
	v_cmp_eq_u16_e64 s[6:7], 2, v11
	v_mov_b32_e32 v0, v129
	v_mov_b32_e32 v1, v129
	v_mov_b32_e32 v2, v129
	v_mov_b32_e32 v3, v129
	v_mov_b32_e32 v4, v129
	v_mov_b32_e32 v5, v129
	v_mov_b32_e32 v6, v129
	v_mov_b32_e32 v7, v129
	v_mov_b32_e32 v8, v129
	v_mov_b32_e32 v11, v129
	v_mov_b32_e32 v12, v129
	v_mov_b32_e32 v13, v129
	v_add_u32_e32 v200, v16, v17
	v_add_u32_e32 v201, v18, v19
	v_add_u32_e32 v203, v21, v22
	v_add_u32_e32 v244, 0xb000, v203
	v_mov_b64_e32 v[30:31], v[14:15]
	s_lshr_b32 s57, s0, 7
	s_or_b32 s58, s56, 31
	v_mov_b32_e32 v204, 0
	v_mov_b64_e32 v[28:29], v[12:13]
	v_mov_b64_e32 v[26:27], v[10:11]
	v_mov_b64_e32 v[24:25], v[8:9]
	v_mov_b64_e32 v[22:23], v[6:7]
	v_mov_b64_e32 v[20:21], v[4:5]
	v_mov_b64_e32 v[18:19], v[2:3]
	v_mov_b64_e32 v[16:17], v[0:1]
	s_branch .LBB0_447

.LBB0_447:
	s_lshl_b32 s59, s57, 7
	s_cmp_lt_u32 s57, 2
	s_waitcnt vmcnt(3)
	ds_write_b128 v200, v[80:83]
	s_waitcnt vmcnt(2)
	ds_write_b128 v200, v[84:87] offset:18432
	s_waitcnt vmcnt(1)
	ds_write_b128 v201, v[88:91]
	s_waitcnt vmcnt(0)
	ds_write_b128 v201, v[92:95] offset:18432
	s_waitcnt lgkmcnt(0)
	s_barrier
	s_cselect_b32 s100, 1, 0
	s_cmp_lt_u32 s99, 0x100
	s_cbranch_scc1 .Lstg_1
	s_sleep 6

.LBB0_484:
	s_cmp_lt_u32 s57, 3
	s_waitcnt vmcnt(3)
	ds_write_b128 v200, v[96:99] offset:45056
	s_waitcnt vmcnt(2)
	ds_write_b128 v200, v[100:103] offset:63488
	s_waitcnt vmcnt(1)
	ds_write_b128 v201, v[104:107] offset:45056
	s_waitcnt vmcnt(0)
	ds_write_b128 v201, v[108:111] offset:63488
	s_waitcnt lgkmcnt(0)
	s_barrier
	s_cselect_b32 s100, 1, 0
	s_cmp_lt_u32 s99, 0x100
	s_cbranch_scc1 .Lstg_0
	s_sleep 6

.LBB0_486:
	s_sub_i32 s0, s59, 63
	s_cmp_le_i32 s0, s56
	s_cselect_b64 s[42:43], -1, 0
	s_cmp_gt_i32 s0, s56
	s_cbranch_scc1 .LBB0_488
	ds_read_b128 v[32:35], v202 offset:58880
	ds_read_b128 v[36:39], v202 offset:58912
	ds_read_b128 v[40:43], v202 offset:58944
	ds_read_b128 v[44:47], v202 offset:58976
	s_waitcnt lgkmcnt(3)
	v_mfma_f32_32x32x16_bf16 v[48:63], v[32:35], v[64:67], 0
	s_waitcnt lgkmcnt(2)
	v_mfma_f32_32x32x16_bf16 v[48:63], v[36:39], v[68:71], v[48:63]
	s_waitcnt lgkmcnt(1)
	v_mfma_f32_32x32x16_bf16 v[48:63], v[40:43], v[72:75], v[48:63]
	s_waitcnt lgkmcnt(0)
	v_mfma_f32_32x32x16_bf16 v[48:63], v[44:47], v[76:79], v[48:63]
.LBB0_488:
	s_addk_i32 s59, 0xff80
	s_or_b32 s17, s59, 33
	s_cmp_le_i32 s17, s56
	s_nop 3
	s_cselect_b64 s[0:1], -1, 0
	s_cmp_gt_i32 s17, s56
	s_cbranch_scc1 .LBB0_490
	ds_read_b128 v[32:35], v202 offset:54272
	ds_read_b128 v[112:115], v202 offset:54304
	ds_read_b128 v[116:119], v202 offset:54336
	ds_read_b128 v[120:123], v202 offset:54368
	s_waitcnt lgkmcnt(3)
	v_mfma_f32_32x32x16_bf16 v[32:47], v[32:35], v[64:67], 0
	s_waitcnt lgkmcnt(2)
	v_mfma_f32_32x32x16_bf16 v[32:47], v[112:115], v[68:71], v[32:47]
	s_waitcnt lgkmcnt(1)
	v_mfma_f32_32x32x16_bf16 v[32:47], v[116:119], v[72:75], v[32:47]
	s_waitcnt lgkmcnt(0)
	v_mfma_f32_32x32x16_bf16 v[32:47], v[120:123], v[76:79], v[32:47]
.LBB0_490:
	s_andn2_b64 vcc, exec, s[42:43]
	s_cbranch_vccnz .LBB0_496
	ds_read_b64_tr_b16 v[126:127], v244 offset:33408
	ds_read_b64_tr_b16 v[120:121], v244 offset:34560
	ds_read_b64_tr_b16 v[112:113], v244 offset:34624
	ds_read_b64_tr_b16 v[118:119], v244 offset:33472
	ds_read_b64_tr_b16 v[124:125], v244 offset:32256
	ds_read_b64_tr_b16 v[122:123], v244 offset:35712
	ds_read_b64_tr_b16 v[116:117], v244 offset:32320
	ds_read_b64_tr_b16 v[114:115], v244 offset:35776
	s_or_b32 s17, s59, 0x60
	s_sub_i32 s60, s56, s17
	s_cmpk_lt_i32 s60, 0x220
	s_mov_b64 s[42:43], -1
	s_cbranch_scc1 .LBB0_562
	s_andn2_b64 vcc, exec, s[42:43]
	s_cbranch_vccz .LBB0_571

.LBB0_497:
	s_cmp_gt_i32 s56, s59
	s_nop 3
	s_cselect_b64 s[42:43], -1, 0
	s_cmp_le_i32 s56, s59
	s_cbranch_scc1 .LBB0_499
	ds_read_b128 v[48:51], v202 offset:49664
	ds_read_b128 v[112:115], v202 offset:49696
	ds_read_b128 v[116:119], v202 offset:49728
	ds_read_b128 v[120:123], v202 offset:49760
	s_waitcnt lgkmcnt(3)
	v_mfma_f32_32x32x16_bf16 v[48:63], v[48:51], v[64:67], 0
	s_waitcnt lgkmcnt(2)
	v_mfma_f32_32x32x16_bf16 v[48:63], v[112:115], v[68:71], v[48:63]
	s_waitcnt lgkmcnt(1)
	v_mfma_f32_32x32x16_bf16 v[48:63], v[116:119], v[72:75], v[48:63]
	s_waitcnt lgkmcnt(0)
	v_mfma_f32_32x32x16_bf16 v[48:63], v[120:123], v[76:79], v[48:63]
.LBB0_499:
	s_andn2_b64 vcc, exec, s[0:1]
	s_cbranch_vccnz .LBB0_505
	ds_read_b64_tr_b16 v[124:125], v244 offset:27648
	ds_read_b64_tr_b16 v[126:127], v244 offset:28800
	ds_read_b64_tr_b16 v[118:119], v244 offset:28864
	ds_read_b64_tr_b16 v[116:117], v244 offset:27712
	ds_read_b64_tr_b16 v[120:121], v244 offset:29952
	ds_read_b64_tr_b16 v[122:123], v244 offset:31104
	ds_read_b64_tr_b16 v[114:115], v244 offset:31168
	ds_read_b64_tr_b16 v[112:113], v244 offset:30016
	s_or_b32 s17, s59, 64
	s_sub_i32 s60, s56, s17
	s_cmpk_gt_i32 s60, 0x21f
	s_mov_b64 s[0:1], -1
	s_cbranch_scc0 .LBB0_572
	s_andn2_b64 vcc, exec, s[0:1]
	s_cbranch_vccz .LBB0_581

.LBB0_506:
	s_cmp_le_i32 s59, s58
	s_nop 3
	s_cselect_b64 s[0:1], -1, 0
	s_cmp_gt_i32 s59, s58
	s_cbranch_scc1 .LBB0_508
	ds_read_b128 v[32:35], v202 offset:45056
	ds_read_b128 v[112:115], v202 offset:45088
	ds_read_b128 v[116:119], v202 offset:45120
	ds_read_b128 v[120:123], v202 offset:45152
	s_waitcnt lgkmcnt(3)
	v_mfma_f32_32x32x16_bf16 v[32:47], v[32:35], v[64:67], 0
	s_waitcnt lgkmcnt(2)
	v_mfma_f32_32x32x16_bf16 v[32:47], v[112:115], v[68:71], v[32:47]
	s_waitcnt lgkmcnt(1)
	v_mfma_f32_32x32x16_bf16 v[32:47], v[116:119], v[72:75], v[32:47]
	s_waitcnt lgkmcnt(0)
	v_mfma_f32_32x32x16_bf16 v[32:47], v[120:123], v[76:79], v[32:47]
.LBB0_508:
	s_andn2_b64 vcc, exec, s[42:43]
	s_cbranch_vccnz .LBB0_515
	ds_read_b64_tr_b16 v[124:125], v244 offset:23040
	ds_read_b64_tr_b16 v[126:127], v244 offset:24192
	ds_read_b64_tr_b16 v[118:119], v244 offset:24256
	ds_read_b64_tr_b16 v[116:117], v244 offset:23104
	ds_read_b64_tr_b16 v[120:121], v244 offset:25344
	ds_read_b64_tr_b16 v[122:123], v244 offset:26496
	ds_read_b64_tr_b16 v[114:115], v244 offset:26560
	ds_read_b64_tr_b16 v[112:113], v244 offset:25408
	s_or_b32 s17, s59, 32
	s_sub_i32 s60, s56, s17
	s_cmpk_gt_i32 s60, 0x21f
	s_mov_b64 s[42:43], -1
	s_cbranch_scc0 .LBB0_582
	s_andn2_b64 vcc, exec, s[42:43]
	s_cbranch_vccz .LBB0_591

.LBB0_516:
	ds_read_b64_tr_b16 v[60:61], v244 offset:18432
	ds_read_b64_tr_b16 v[62:63], v244 offset:19584
	ds_read_b64_tr_b16 v[54:55], v244 offset:19648
	ds_read_b64_tr_b16 v[52:53], v244 offset:18496
	ds_read_b64_tr_b16 v[56:57], v244 offset:20736
	ds_read_b64_tr_b16 v[58:59], v244 offset:21888
	ds_read_b64_tr_b16 v[50:51], v244 offset:21952
	ds_read_b64_tr_b16 v[48:49], v244 offset:20800
	s_sub_i32 s17, s56, s59
	s_cmpk_gt_i32 s17, 0x21f
	s_mov_b64 s[0:1], -1
	s_cbranch_scc0 .LBB0_592
	s_andn2_b64 vcc, exec, s[0:1]
	s_cbranch_vccz .LBB0_601

	.amdhsa_kernel _Z4mega6Paramsii
		.amdhsa_group_segment_fixed_size 0
		.amdhsa_private_segment_fixed_size 0
		.amdhsa_kernarg_size 424
		.amdhsa_user_sgpr_count 2
		.amdhsa_user_sgpr_dispatch_ptr 0
		.amdhsa_user_sgpr_queue_ptr 0
		.amdhsa_user_sgpr_kernarg_segment_ptr 1
		.amdhsa_user_sgpr_dispatch_id 0
		.amdhsa_user_sgpr_kernarg_preload_length 0
		.amdhsa_user_sgpr_kernarg_preload_offset 0
		.amdhsa_user_sgpr_private_segment_size 0
		.amdhsa_uses_dynamic_stack 0
		.amdhsa_enable_private_segment 0
		.amdhsa_system_sgpr_workgroup_id_x 1
		.amdhsa_system_sgpr_workgroup_id_y 0
		.amdhsa_system_sgpr_workgroup_id_z 0
		.amdhsa_system_sgpr_workgroup_info 0
		.amdhsa_system_vgpr_workitem_id 2
		.amdhsa_next_free_vgpr 245
		.amdhsa_next_free_sgpr 101
		.amdhsa_accum_offset 248
		.amdhsa_reserve_vcc 1
		.amdhsa_float_round_mode_32 0
		.amdhsa_float_round_mode_16_64 0
		.amdhsa_float_denorm_mode_32 3
		.amdhsa_float_denorm_mode_16_64 3
		.amdhsa_dx10_clamp 1
		.amdhsa_ieee_mode 1
		.amdhsa_fp16_overflow 0
		.amdhsa_tg_split 0
		.amdhsa_exception_fp_ieee_invalid_op 0
		.amdhsa_exception_fp_denorm_src 0
		.amdhsa_exception_fp_ieee_div_zero 0
		.amdhsa_exception_fp_ieee_overflow 0
		.amdhsa_exception_fp_ieee_underflow 0
		.amdhsa_exception_fp_ieee_inexact 0
		.amdhsa_exception_int_div_zero 0
	.end_amdhsa_kernel

amdhsa.kernels:
  - .agpr_count:     0
    .args:
      - .offset:         0
        .size:           160
        .value_kind:     by_value
      - .offset:         160
        .size:           4
        .value_kind:     by_value
      - .offset:         164
        .size:           4
        .value_kind:     by_value
      - .offset:         168
        .size:           4
        .value_kind:     hidden_block_count_x
      - .offset:         172
        .size:           4
        .value_kind:     hidden_block_count_y
      - .offset:         176
        .size:           4
        .value_kind:     hidden_block_count_z
      - .offset:         180
        .size:           2
        .value_kind:     hidden_group_size_x
      - .offset:         182
        .size:           2
        .value_kind:     hidden_group_size_y
      - .offset:         184
        .size:           2
        .value_kind:     hidden_group_size_z
      - .offset:         186
        .size:           2
        .value_kind:     hidden_remainder_x
      - .offset:         188
        .size:           2
        .value_kind:     hidden_remainder_y
      - .offset:         190
        .size:           2
        .value_kind:     hidden_remainder_z
      - .offset:         208
        .size:           8
        .value_kind:     hidden_global_offset_x
      - .offset:         216
        .size:           8
        .value_kind:     hidden_global_offset_y
      - .offset:         224
        .size:           8
        .value_kind:     hidden_global_offset_z
      - .offset:         232
        .size:           2
        .value_kind:     hidden_grid_dims
      - .offset:         256
        .size:           8
        .value_kind:     hidden_multigrid_sync_arg
      - .offset:         288
        .size:           4
        .value_kind:     hidden_dynamic_lds_size
    .group_segment_fixed_size: 0
    .kernarg_segment_align: 8
    .kernarg_segment_size: 424
    .language:       OpenCL C
    .language_version:
      - 2
      - 0
    .max_flat_workgroup_size: 512
    .name:           _Z4mega6Paramsii
    .private_segment_fixed_size: 0
    .sgpr_count:     107
    .sgpr_spill_count: 3
    .symbol:         _Z4mega6Paramsii.kd
    .uniform_work_group_size: 1
    .uses_dynamic_stack: false
    .vgpr_count:     245
    .vgpr_spill_count: 0
    .wavefront_size: 64
